# fast C attention loop: exps write P to a separate register block, previous tile row-sum adds interleaved under the QK MFMAs
# baseline (speedup 1.0000x reference)
.LBB0_159:
	s_or_b64 exec, exec, s[14:15]
	global_load_dwordx4 v[124:127], v[10:11], off offset:128
	s_movk_i32 s6, 0xd0
	v_mul_lo_u32 v9, v12, s6
	v_lshl_add_u32 v157, v6, 4, v9
	v_mul_lo_u32 v6, v7, s6
	v_lshl_add_u32 v158, v8, 4, v6
	s_waitcnt vmcnt(3)
	ds_write_b128 v157, v[104:107]
	s_and_saveexec_b64 s[12:13], s[38:39]
	ds_write_b128 v158, v[112:115]
	s_or_b64 exec, exec, s[12:13]
	v_mad_i64_i32 v[6:7], s[12:13], v156, s54, 0
	s_and_b64 s[12:13], s[88:89], exec
	s_cselect_b32 s14, 0x84, 4
	v_lshl_add_u64 v[6:7], s[2:3], 0, v[6:7]
	s_add_u32 s2, s52, s96
	v_lshl_add_u64 v[6:7], v[6:7], 0, v[0:1]
	s_addc_u32 s3, s53, 0
	v_lshl_add_u64 v[150:151], s[2:3], 0, v[6:7]
	s_add_u32 s2, s40, s41
	v_and_b32_e32 v8, 31, v148
	s_addc_u32 s3, s23, 0
	v_mul_u32_u24_e32 v16, 0xd0, v8
	v_lshlrev_b32_e32 v8, 6, v8
	v_cmp_lt_i32_e32 vcc, v207, v206
	s_add_u32 s2, s52, s2
	v_mul_lo_u32 v9, v156, s4
	v_sub_u32_e32 v17, v16, v8
	v_cndmask_b32_e32 v8, v205, v207, vcc
	s_addc_u32 s3, s53, s3
	v_mov_b32_e32 v14, v1
	v_mov_b32_e32 v15, v1
	v_lshl_add_u32 v160, v140, 4, v9
	v_lshlrev_b32_e32 v159, 2, v8
	v_lshl_add_u64 v[152:153], v[2:3], 1, s[2:3]
	v_lshl_add_u64 v[154:155], v[4:5], 1, s[2:3]
	v_mov_b32_e32 v0, v1
	v_mov_b32_e32 v2, v1
	v_mov_b32_e32 v3, v1
	v_mov_b32_e32 v4, v1
	v_mov_b32_e32 v5, v1
	v_mov_b32_e32 v6, v1
	v_mov_b32_e32 v7, v1
	v_mov_b32_e32 v8, v1
	v_mov_b32_e32 v9, v1
	v_mov_b32_e32 v10, v1
	v_mov_b32_e32 v11, v1
	v_mov_b32_e32 v12, v1
	v_mov_b32_e32 v13, v1
	v_add_u32_e32 v164, v16, v130
	v_add_u32_e32 v165, v17, v130
	v_mov_b64_e32 v[30:31], v[14:15]
	v_mov_b64_e32 v[46:47], v[14:15]
	s_mov_b32 s22, 0
	v_mov_b32_e32 v161, 0
	v_bfrev_b32_e32 v218, 1
	v_mov_b32_e32 v219, v218
	v_mov_b32_e32 v220, v218
	v_mov_b32_e32 v221, v218
	v_mov_b32_e32 v222, v218
	v_mov_b32_e32 v223, v218
	v_mov_b32_e32 v224, v218
	v_mov_b32_e32 v225, v218
	v_mov_b32_e32 v226, v218
	v_mov_b32_e32 v227, v218
	v_mov_b32_e32 v228, v218
	v_mov_b32_e32 v229, v218
	v_mov_b32_e32 v230, v218
	v_mov_b32_e32 v231, v218
	v_mov_b32_e32 v232, v218
	v_mov_b32_e32 v233, v218
	v_mov_b64_e32 v[28:29], v[12:13]
	v_mov_b64_e32 v[26:27], v[10:11]
	v_mov_b64_e32 v[24:25], v[8:9]
	v_mov_b64_e32 v[22:23], v[6:7]
	v_mov_b64_e32 v[20:21], v[4:5]
	v_mov_b64_e32 v[18:19], v[2:3]
	v_mov_b64_e32 v[16:17], v[0:1]
	v_mov_b64_e32 v[44:45], v[12:13]
	v_mov_b64_e32 v[42:43], v[10:11]
	v_mov_b64_e32 v[40:41], v[8:9]
	v_mov_b64_e32 v[38:39], v[6:7]
	v_mov_b64_e32 v[36:37], v[4:5]
	v_mov_b64_e32 v[34:35], v[2:3]
	v_mov_b64_e32 v[32:33], v[0:1]
	v_mov_b32_e32 v0, 0
	s_waitcnt vmcnt(2)
	ds_write_b128 v160, v[120:123] offset:13312
	s_waitcnt lgkmcnt(0)
	s_barrier
	s_cmp_lg_u32 s98, 0
	s_cbranch_scc1 .LBB0_162_sl
	v_mov_b32_e32 v184, 0
	v_mov_b32_e32 v185, 0
	v_mov_b32_e32 v186, 0
	v_mov_b32_e32 v187, 0
	v_mov_b32_e32 v188, 0
	v_mov_b32_e32 v189, 0
	v_mov_b32_e32 v190, 0
	v_mov_b32_e32 v191, 0
	v_mov_b32_e32 v192, 0
	v_mov_b32_e32 v193, 0
	v_mov_b32_e32 v194, 0
	v_mov_b32_e32 v195, 0
	v_mov_b32_e32 v196, 0
	v_mov_b32_e32 v197, 0
	v_mov_b32_e32 v198, 0
	v_mov_b32_e32 v199, 0
	v_mov_b32_e32 v246, 0
	v_mov_b32_e32 v247, 0
	v_mov_b32_e32 v248, 0
	v_mov_b32_e32 v249, 0
	v_mov_b32_e32 v250, 0
	v_mov_b32_e32 v251, 0
	v_mov_b32_e32 v252, 0
	v_mov_b32_e32 v234, 0
	v_mov_b32_e32 v235, 0
	v_mov_b32_e32 v203, 0
	v_mov_b32_e32 v204, 0
	v_mov_b32_e32 v208, 0
	v_mov_b32_e32 v209, 0
	v_mov_b32_e32 v210, 0
	v_mov_b32_e32 v211, 0
	v_mov_b32_e32 v214, 0
	v_lshl_add_u64 v[236:237], v[152:153], 0, s[20:21]
	v_lshl_add_u64 v[240:241], v[154:155], 0, s[20:21]
	v_lshl_add_u64 v[244:245], v[150:151], 0, s[20:21]
	s_mov_b32 s2, 0x9186800
	s_mov_b32 s3, 0
	v_lshl_add_u64 v[238:239], v[236:237], 0, s[2:3]
	v_lshl_add_u64 v[242:243], v[240:241], 0, s[2:3]
	s_mov_b32 s2, 0x9183800
	v_lshl_add_u64 v[236:237], v[236:237], 0, s[2:3]
	v_lshl_add_u64 v[240:241], v[240:241], 0, s[2:3]
	s_mov_b32 s2, 0xa40d900
	v_lshl_add_u64 v[244:245], v[244:245], 0, s[2:3]

.LBB0_166:
	ds_read_b128 v[2:5], v164
	ds_read_b128 v[6:9], v164 offset:32
	ds_read_b128 v[10:13], v164 offset:6656
	ds_read_b128 v[128:131], v164 offset:6688
	ds_read_b128 v[132:135], v164 offset:64
	ds_read_b128 v[136:139], v164 offset:96
	ds_read_b128 v[140:143], v164 offset:6720
	ds_read_b128 v[144:147], v164 offset:6752
	ds_read_b128 v[166:169], v164 offset:128
	ds_read_b128 v[170:173], v164 offset:160
	ds_read_b128 v[174:177], v164 offset:6784
	ds_read_b128 v[178:181], v164 offset:6816
	s_cmp_eq_u32 s22, 0
	s_cselect_b64 s[40:41], -1, 0
	s_waitcnt lgkmcnt(11)
	s_nop 0
	v_mfma_f32_32x32x16_bf16 v[64:79], v[2:5], v[80:83], v[218:233]
	s_waitcnt lgkmcnt(9)
	v_mfma_f32_32x32x16_bf16 v[48:63], v[10:13], v[80:83], v[218:233]
	v_add_f32_e32 v162, 0, v184
	v_add_f32_e32 v163, 0, v246
	v_add_f32_e32 v162, v162, v185
	v_add_f32_e32 v163, v163, v247
	v_mfma_f32_32x32x16_bf16 v[64:79], v[6:9], v[84:87], v[64:79]
	v_add_f32_e32 v162, v186, v162
	v_add_f32_e32 v163, v248, v163
	v_add_f32_e32 v162, v187, v162
	v_add_f32_e32 v163, v249, v163
	s_waitcnt lgkmcnt(8)
	v_mfma_f32_32x32x16_bf16 v[48:63], v[128:131], v[84:87], v[48:63]
	v_add_f32_e32 v162, v188, v162
	v_add_f32_e32 v163, v250, v163
	v_add_f32_e32 v162, v189, v162
	v_add_f32_e32 v163, v251, v163
	s_waitcnt lgkmcnt(7)
	v_mfma_f32_32x32x16_bf16 v[64:79], v[132:135], v[88:91], v[64:79]
	v_add_f32_e32 v162, v190, v162
	v_add_f32_e32 v163, v252, v163
	v_add_f32_e32 v162, v191, v162
	v_add_f32_e32 v163, v234, v163
	s_waitcnt lgkmcnt(5)
	v_mfma_f32_32x32x16_bf16 v[48:63], v[140:143], v[88:91], v[48:63]
	v_add_f32_e32 v162, v192, v162
	v_add_f32_e32 v163, v235, v163
	v_add_f32_e32 v162, v193, v162
	v_add_f32_e32 v163, v203, v163
	v_mfma_f32_32x32x16_bf16 v[64:79], v[136:139], v[92:95], v[64:79]
	v_add_f32_e32 v162, v194, v162
	v_add_f32_e32 v163, v204, v163
	v_add_f32_e32 v162, v195, v162
	v_add_f32_e32 v163, v208, v163
	s_waitcnt lgkmcnt(4)
	v_mfma_f32_32x32x16_bf16 v[48:63], v[144:147], v[92:95], v[48:63]
	v_add_f32_e32 v162, v196, v162
	v_add_f32_e32 v163, v209, v163
	v_add_f32_e32 v162, v197, v162
	v_add_f32_e32 v163, v210, v163
	ds_read_b128 v[144:147], v165 offset:13312
	ds_read_b128 v[140:143], v165 offset:13344
	ds_read_b128 v[136:139], v165 offset:13376
	ds_read_b128 v[132:135], v165 offset:13408
	ds_read_b128 v[128:131], v165 offset:17920
	ds_read_b128 v[10:13], v165 offset:17952
	ds_read_b128 v[2:5], v165 offset:17984
	ds_read_b128 v[6:9], v165 offset:18016
	s_waitcnt lgkmcnt(11)
	v_mfma_f32_32x32x16_bf16 v[64:79], v[166:169], v[96:99], v[64:79]
	v_add_f32_e32 v162, v198, v162
	v_add_f32_e32 v163, v211, v163
	v_add_f32_e32 v162, v199, v162
	v_add_f32_e32 v163, v214, v163
	s_waitcnt lgkmcnt(9)
	v_mfma_f32_32x32x16_bf16 v[48:63], v[174:177], v[96:99], v[48:63]
	v_add_f32_e32 v162, v163, v162
	v_add_f32_e32 v0, v0, v162
	v_mfma_f32_32x32x16_bf16 v[64:79], v[170:173], v[100:103], v[64:79]
	s_waitcnt lgkmcnt(8)
	v_mfma_f32_32x32x16_bf16 v[48:63], v[178:181], v[100:103], v[48:63]
	s_nop 9
	s_and_b64 vcc, exec, s[40:41]
	s_cbranch_vccz .LBB0_168
	s_nop 9
	v_max_f32_e32 v166, v49, v49
	v_max_f32_e32 v167, v65, v65
	v_max_f32_e32 v166, v167, v166
	v_max_f32_e32 v167, v50, v50
	v_max_f32_e32 v168, v66, v66
	v_max_f32_e32 v167, v168, v167
	v_max_f32_e32 v168, v51, v51
	v_max_f32_e32 v169, v67, v67
	v_max3_f32 v166, v64, v48, v166
	v_max_f32_e32 v168, v169, v168
	v_max3_f32 v166, v166, v167, v168
	v_max_f32_e32 v167, v52, v52
	v_max_f32_e32 v168, v68, v68
	v_max_f32_e32 v167, v168, v167
	v_max_f32_e32 v168, v53, v53
	v_max_f32_e32 v169, v69, v69
	v_max_f32_e32 v168, v169, v168
	v_max3_f32 v166, v166, v167, v168
	v_max_f32_e32 v167, v54, v54
	v_max_f32_e32 v168, v70, v70
	v_max_f32_e32 v167, v168, v167
	v_max_f32_e32 v168, v55, v55
	v_max_f32_e32 v169, v71, v71
	v_max_f32_e32 v168, v169, v168
	v_max3_f32 v166, v166, v167, v168
	v_max_f32_e32 v167, v56, v56
	v_max_f32_e32 v168, v72, v72
	v_max_f32_e32 v167, v168, v167
	v_max_f32_e32 v168, v57, v57
	v_max_f32_e32 v169, v73, v73
	v_max_f32_e32 v168, v169, v168
	v_max3_f32 v166, v166, v167, v168
	v_max_f32_e32 v167, v58, v58
	v_max_f32_e32 v168, v74, v74
	v_max_f32_e32 v167, v168, v167
	v_max_f32_e32 v168, v59, v59
	v_max_f32_e32 v169, v75, v75
	v_max_f32_e32 v168, v169, v168
	v_max3_f32 v166, v166, v167, v168
	v_max_f32_e32 v167, v60, v60
	v_max_f32_e32 v168, v76, v76
	v_max_f32_e32 v167, v168, v167
	v_max_f32_e32 v168, v61, v61
	v_max_f32_e32 v169, v77, v77
	v_max_f32_e32 v168, v169, v168
	v_max3_f32 v166, v166, v167, v168
	v_max_f32_e32 v167, v62, v62
	v_max_f32_e32 v168, v78, v78
	v_max_f32_e32 v167, v168, v167
	v_max_f32_e32 v168, v63, v63
	v_max_f32_e32 v169, v79, v79
	v_max_f32_e32 v168, v169, v168
	v_max3_f32 v166, v166, v167, v168
	ds_bpermute_b32 v167, v159, v166
	v_mov_b32_e32 v168, v64
	v_mov_b32_e32 v64, v65
	v_mov_b32_e32 v65, v66
	v_mov_b32_e32 v66, v67
	s_waitcnt lgkmcnt(0)
	v_max_f32_e32 v167, v167, v167
	v_max_f32_e32 v166, v166, v167
	v_max_f32_e32 v167, 0, v166
	v_cndmask_b32_e64 v166, v167, v166, s[40:41]
	v_exp_f32_e64 v167, -v166
	v_mov_b32_e32 v67, v68
	v_mov_b32_e32 v169, v48
	v_add_f32_e32 v161, v161, v166
	v_xor_b32_e32 v218, 0x80000000, v161
	v_mov_b32_e32 v219, v218
	v_mov_b32_e32 v220, v218
	v_mov_b32_e32 v221, v218
	v_mov_b32_e32 v222, v218
	v_mov_b32_e32 v223, v218
	v_mov_b32_e32 v224, v218
	v_mov_b32_e32 v225, v218
	v_mov_b32_e32 v226, v218
	v_mov_b32_e32 v227, v218
	v_mov_b32_e32 v228, v218
	v_mov_b32_e32 v229, v218
	v_mov_b32_e32 v230, v218
	v_mov_b32_e32 v231, v218
	v_mov_b32_e32 v232, v218
	v_mov_b32_e32 v233, v218
	v_pk_add_f32 v[170:171], v[64:65], v[166:167] op_sel_hi:[1,0] neg_lo:[0,1] neg_hi:[0,1]
	v_mov_b32_e32 v65, v50
	v_mov_b32_e32 v50, v51
	v_mov_b32_e32 v51, v52
	v_pk_add_f32 v[172:173], v[66:67], v[166:167] op_sel_hi:[1,0] neg_lo:[0,1] neg_hi:[0,1]
	v_pk_add_f32 v[66:67], v[50:51], v[166:167] op_sel_hi:[1,0] neg_lo:[0,1] neg_hi:[0,1]
	v_mov_b32_e32 v50, v69
	v_mov_b32_e32 v51, v70
	v_pk_add_f32 v[174:175], v[50:51], v[166:167] op_sel_hi:[1,0] neg_lo:[0,1] neg_hi:[0,1]
	v_mov_b32_e32 v50, v53
	v_mov_b32_e32 v51, v54
	v_pk_add_f32 v[68:69], v[50:51], v[166:167] op_sel_hi:[1,0] neg_lo:[0,1] neg_hi:[0,1]
	v_mov_b32_e32 v50, v71
	v_mov_b32_e32 v51, v72
	v_pk_add_f32 v[176:177], v[50:51], v[166:167] op_sel_hi:[1,0] neg_lo:[0,1] neg_hi:[0,1]
	v_mov_b32_e32 v50, v55
	v_mov_b32_e32 v51, v56
	v_pk_add_f32 v[70:71], v[50:51], v[166:167] op_sel_hi:[1,0] neg_lo:[0,1] neg_hi:[0,1]
	v_mov_b32_e32 v50, v73
	v_mov_b32_e32 v51, v74
	v_pk_add_f32 v[178:179], v[50:51], v[166:167] op_sel_hi:[1,0] neg_lo:[0,1] neg_hi:[0,1]
	v_mov_b32_e32 v50, v57
	v_mov_b32_e32 v51, v58
	v_pk_add_f32 v[72:73], v[50:51], v[166:167] op_sel_hi:[1,0] neg_lo:[0,1] neg_hi:[0,1]
	v_mov_b32_e32 v50, v75
	v_mov_b32_e32 v51, v76
	v_pk_add_f32 v[180:181], v[50:51], v[166:167] op_sel_hi:[1,0] neg_lo:[0,1] neg_hi:[0,1]
	v_mov_b32_e32 v50, v59
	v_mov_b32_e32 v51, v60
	v_pk_add_f32 v[74:75], v[50:51], v[166:167] op_sel_hi:[1,0] neg_lo:[0,1] neg_hi:[0,1]
	v_mov_b32_e32 v50, v77
	v_mov_b32_e32 v51, v78
	v_mov_b32_e32 v64, v49
	v_pk_add_f32 v[182:183], v[50:51], v[166:167] op_sel_hi:[1,0] neg_lo:[0,1] neg_hi:[0,1]
	v_mov_b32_e32 v50, v61
	v_mov_b32_e32 v51, v62
	v_cndmask_b32_e64 v48, v167, 1.0, s[40:41]
	v_pk_add_f32 v[168:169], v[168:169], v[166:167] op_sel_hi:[1,0] neg_lo:[0,1] neg_hi:[0,1]
	v_pk_add_f32 v[64:65], v[64:65], v[166:167] op_sel_hi:[1,0] neg_lo:[0,1] neg_hi:[0,1]
	v_pk_add_f32 v[76:77], v[50:51], v[166:167] op_sel_hi:[1,0] neg_lo:[0,1] neg_hi:[0,1]
	v_mul_f32_e32 v0, v0, v48
	v_pk_mul_f32 v[46:47], v[46:47], v[48:49] op_sel_hi:[1,0]
	v_pk_mul_f32 v[44:45], v[44:45], v[48:49] op_sel_hi:[1,0]
	v_pk_mul_f32 v[42:43], v[42:43], v[48:49] op_sel_hi:[1,0]
	v_pk_mul_f32 v[40:41], v[40:41], v[48:49] op_sel_hi:[1,0]
	v_pk_mul_f32 v[38:39], v[38:39], v[48:49] op_sel_hi:[1,0]
	v_pk_mul_f32 v[36:37], v[36:37], v[48:49] op_sel_hi:[1,0]
	v_pk_mul_f32 v[34:35], v[34:35], v[48:49] op_sel_hi:[1,0]
	v_pk_mul_f32 v[32:33], v[32:33], v[48:49] op_sel_hi:[1,0]
	v_pk_mul_f32 v[30:31], v[30:31], v[48:49] op_sel_hi:[1,0]
	v_pk_mul_f32 v[28:29], v[28:29], v[48:49] op_sel_hi:[1,0]
	v_pk_mul_f32 v[26:27], v[26:27], v[48:49] op_sel_hi:[1,0]
	v_pk_mul_f32 v[24:25], v[24:25], v[48:49] op_sel_hi:[1,0]
	v_pk_mul_f32 v[22:23], v[22:23], v[48:49] op_sel_hi:[1,0]
	v_pk_mul_f32 v[20:21], v[20:21], v[48:49] op_sel_hi:[1,0]
	v_pk_mul_f32 v[18:19], v[18:19], v[48:49] op_sel_hi:[1,0]
	v_pk_mul_f32 v[16:17], v[16:17], v[48:49] op_sel_hi:[1,0]
	v_sub_f32_e32 v79, v79, v166
	v_sub_f32_e32 v63, v63, v166
	v_mov_b32_e32 v49, v64
	v_mov_b32_e32 v50, v65
	v_mov_b32_e32 v51, v66
	v_mov_b32_e32 v52, v67
	v_mov_b32_e32 v53, v68
	v_mov_b32_e32 v54, v69
	v_mov_b32_e32 v55, v70
	v_mov_b32_e32 v56, v71
	v_mov_b32_e32 v57, v72
	v_mov_b32_e32 v58, v73
	v_mov_b32_e32 v59, v74
	v_mov_b32_e32 v60, v75
	v_mov_b32_e32 v61, v76
	v_mov_b32_e32 v62, v77
	v_mov_b32_e32 v65, v170
	v_mov_b32_e32 v66, v171
	v_mov_b32_e32 v67, v172
	v_mov_b32_e32 v68, v173
	v_mov_b32_e32 v69, v174
	v_mov_b32_e32 v70, v175
	v_mov_b32_e32 v71, v176
	v_mov_b32_e32 v72, v177
	v_mov_b32_e32 v73, v178
	v_mov_b32_e32 v74, v179
	v_mov_b32_e32 v75, v180
	v_mov_b32_e32 v76, v181
	v_mov_b32_e32 v77, v182
	v_mov_b32_e32 v78, v183
	v_mov_b32_e32 v64, v168
	v_mov_b32_e32 v48, v169
.LBB0_168:
	v_exp_f32_e32 v184, v64
	v_exp_f32_e32 v185, v65
	v_exp_f32_e32 v186, v66
	v_exp_f32_e32 v187, v67
	v_exp_f32_e32 v188, v68
	v_exp_f32_e32 v189, v69
	v_exp_f32_e32 v190, v70
	v_exp_f32_e32 v191, v71
	v_cvt_pk_bf16_f32 v166, v184, v185
	v_cvt_pk_bf16_f32 v167, v186, v187
	v_cvt_pk_bf16_f32 v168, v188, v189
	v_cvt_pk_bf16_f32 v169, v190, v191
	v_exp_f32_e32 v192, v72
	v_exp_f32_e32 v193, v73
	s_waitcnt lgkmcnt(0)
	v_mfma_f32_32x32x16_bf16 v[32:47], v[144:147], v[166:169], v[32:47]
	v_exp_f32_e32 v194, v74
	v_exp_f32_e32 v195, v75
	v_exp_f32_e32 v196, v76
	v_exp_f32_e32 v197, v77
	v_exp_f32_e32 v198, v78
	v_exp_f32_e32 v199, v79
	v_cvt_pk_bf16_f32 v170, v192, v193
	v_mfma_f32_32x32x16_bf16 v[16:31], v[128:131], v[166:169], v[16:31]
	v_cvt_pk_bf16_f32 v171, v194, v195
	v_cvt_pk_bf16_f32 v172, v196, v197
	v_cvt_pk_bf16_f32 v173, v198, v199
	v_exp_f32_e32 v246, v48
	v_exp_f32_e32 v247, v49
	v_exp_f32_e32 v248, v50
	v_exp_f32_e32 v249, v51
	v_mfma_f32_32x32x16_bf16 v[32:47], v[140:143], v[170:173], v[32:47]
	v_exp_f32_e32 v250, v52
	v_exp_f32_e32 v251, v53
	v_exp_f32_e32 v252, v54
	v_exp_f32_e32 v234, v55
	v_cvt_pk_bf16_f32 v174, v246, v247
	v_cvt_pk_bf16_f32 v175, v248, v249
	v_cvt_pk_bf16_f32 v176, v250, v251
	v_mfma_f32_32x32x16_bf16 v[16:31], v[10:13], v[170:173], v[16:31]
	v_cvt_pk_bf16_f32 v177, v252, v234
	v_exp_f32_e32 v235, v56
	v_exp_f32_e32 v203, v57
	v_exp_f32_e32 v204, v58
	v_exp_f32_e32 v208, v59
	v_exp_f32_e32 v209, v60
	v_exp_f32_e32 v210, v61
	v_mfma_f32_32x32x16_bf16 v[32:47], v[136:139], v[174:177], v[32:47]
	v_exp_f32_e32 v211, v62
	v_exp_f32_e32 v214, v63
	v_cvt_pk_bf16_f32 v178, v235, v203
	v_cvt_pk_bf16_f32 v179, v204, v208
	v_cvt_pk_bf16_f32 v180, v209, v210
	v_cvt_pk_bf16_f32 v181, v211, v214
	s_waitcnt vmcnt(1)
	ds_write_b128 v157, v[116:119] offset:22528
	v_mfma_f32_32x32x16_bf16 v[16:31], v[2:5], v[174:177], v[16:31]
	v_mfma_f32_32x32x16_bf16 v[32:47], v[132:135], v[178:181], v[32:47]
	v_mfma_f32_32x32x16_bf16 v[16:31], v[6:9], v[178:181], v[16:31]
	s_and_saveexec_b64 s[12:13], s[38:39]
	ds_write_b128 v158, v[108:111] offset:22528
	s_or_b64 exec, exec, s[12:13]
	s_add_i32 s12, s22, 3
	s_cmp_ge_u32 s12, s14
	s_waitcnt vmcnt(0)
	ds_write_b128 v160, v[124:127] offset:35840
	s_waitcnt lgkmcnt(0)
	s_barrier
	s_cbranch_scc1 .LBB0_174
	global_load_dwordx4 v[116:119], v[238:239], off
	s_and_saveexec_b64 s[12:13], s[38:39]
	s_cbranch_execz .LBB0_173
	global_load_dwordx4 v[108:111], v[242:243], off

.LBB0_174:
	ds_read_b128 v[2:5], v164 offset:22528
	ds_read_b128 v[6:9], v164 offset:22560
	ds_read_b128 v[10:13], v164 offset:29184
	ds_read_b128 v[128:131], v164 offset:29216
	ds_read_b128 v[132:135], v164 offset:22592
	ds_read_b128 v[136:139], v164 offset:22624
	ds_read_b128 v[140:143], v164 offset:29248
	ds_read_b128 v[144:147], v164 offset:29280
	ds_read_b128 v[166:169], v164 offset:22656
	ds_read_b128 v[170:173], v164 offset:22688
	ds_read_b128 v[174:177], v164 offset:29312
	ds_read_b128 v[178:181], v164 offset:29344
	s_waitcnt lgkmcnt(11)
	s_nop 0
	v_mfma_f32_32x32x16_bf16 v[64:79], v[2:5], v[80:83], v[218:233]
	s_waitcnt lgkmcnt(9)
	v_mfma_f32_32x32x16_bf16 v[48:63], v[10:13], v[80:83], v[218:233]
	v_add_f32_e32 v162, 0, v184
	v_add_f32_e32 v163, 0, v246
	v_add_f32_e32 v162, v162, v185
	v_add_f32_e32 v163, v163, v247
	v_mfma_f32_32x32x16_bf16 v[64:79], v[6:9], v[84:87], v[64:79]
	v_add_f32_e32 v162, v186, v162
	v_add_f32_e32 v163, v248, v163
	v_add_f32_e32 v162, v187, v162
	v_add_f32_e32 v163, v249, v163
	s_waitcnt lgkmcnt(8)
	v_mfma_f32_32x32x16_bf16 v[48:63], v[128:131], v[84:87], v[48:63]
	v_add_f32_e32 v162, v188, v162
	v_add_f32_e32 v163, v250, v163
	v_add_f32_e32 v162, v189, v162
	v_add_f32_e32 v163, v251, v163
	s_waitcnt lgkmcnt(7)
	v_mfma_f32_32x32x16_bf16 v[64:79], v[132:135], v[88:91], v[64:79]
	v_add_f32_e32 v162, v190, v162
	v_add_f32_e32 v163, v252, v163
	v_add_f32_e32 v162, v191, v162
	v_add_f32_e32 v163, v234, v163
	s_waitcnt lgkmcnt(5)
	v_mfma_f32_32x32x16_bf16 v[48:63], v[140:143], v[88:91], v[48:63]
	v_add_f32_e32 v162, v192, v162
	v_add_f32_e32 v163, v235, v163
	v_add_f32_e32 v162, v193, v162
	v_add_f32_e32 v163, v203, v163
	v_mfma_f32_32x32x16_bf16 v[64:79], v[136:139], v[92:95], v[64:79]
	v_add_f32_e32 v162, v194, v162
	v_add_f32_e32 v163, v204, v163
	v_add_f32_e32 v162, v195, v162
	v_add_f32_e32 v163, v208, v163
	s_waitcnt lgkmcnt(4)
	v_mfma_f32_32x32x16_bf16 v[48:63], v[144:147], v[92:95], v[48:63]
	v_add_f32_e32 v162, v196, v162
	v_add_f32_e32 v163, v209, v163
	v_add_f32_e32 v162, v197, v162
	v_add_f32_e32 v163, v210, v163
	ds_read_b128 v[144:147], v165 offset:35840
	ds_read_b128 v[140:143], v165 offset:35872
	ds_read_b128 v[136:139], v165 offset:35904
	ds_read_b128 v[132:135], v165 offset:35936
	ds_read_b128 v[128:131], v165 offset:40448
	ds_read_b128 v[10:13], v165 offset:40480
	ds_read_b128 v[2:5], v165 offset:40512
	ds_read_b128 v[6:9], v165 offset:40544
	s_waitcnt lgkmcnt(11)
	v_mfma_f32_32x32x16_bf16 v[64:79], v[166:169], v[96:99], v[64:79]
	v_add_f32_e32 v162, v198, v162
	v_add_f32_e32 v163, v211, v163
	v_add_f32_e32 v162, v199, v162
	v_add_f32_e32 v163, v214, v163
	s_waitcnt lgkmcnt(9)
	v_mfma_f32_32x32x16_bf16 v[48:63], v[174:177], v[96:99], v[48:63]
	v_add_f32_e32 v162, v163, v162
	v_add_f32_e32 v0, v0, v162
	v_mfma_f32_32x32x16_bf16 v[64:79], v[170:173], v[100:103], v[64:79]
	s_waitcnt lgkmcnt(8)
	v_mfma_f32_32x32x16_bf16 v[48:63], v[178:181], v[100:103], v[48:63]
	s_nop 10
.LBB0_176:
	v_exp_f32_e32 v184, v64
	v_exp_f32_e32 v246, v48
	v_exp_f32_e32 v185, v65
	v_exp_f32_e32 v186, v66
	v_exp_f32_e32 v187, v67
	v_exp_f32_e32 v188, v68
	v_exp_f32_e32 v189, v69
	v_exp_f32_e32 v190, v70
	v_exp_f32_e32 v191, v71
	v_cvt_pk_bf16_f32 v166, v184, v185
	v_cvt_pk_bf16_f32 v167, v186, v187
	v_cvt_pk_bf16_f32 v168, v188, v189
	v_cvt_pk_bf16_f32 v169, v190, v191
	v_exp_f32_e32 v192, v72
	v_exp_f32_e32 v193, v73
	s_waitcnt lgkmcnt(0)
	v_mfma_f32_32x32x16_bf16 v[32:47], v[144:147], v[166:169], v[32:47]
	v_exp_f32_e32 v194, v74
	v_exp_f32_e32 v195, v75
	v_exp_f32_e32 v196, v76
	v_exp_f32_e32 v197, v77
	v_exp_f32_e32 v198, v78
	v_exp_f32_e32 v199, v79
	v_cvt_pk_bf16_f32 v170, v192, v193
	v_mfma_f32_32x32x16_bf16 v[16:31], v[128:131], v[166:169], v[16:31]
	v_cvt_pk_bf16_f32 v171, v194, v195
	v_cvt_pk_bf16_f32 v172, v196, v197
	v_cvt_pk_bf16_f32 v173, v198, v199
	v_exp_f32_e32 v247, v49
	v_exp_f32_e32 v248, v50
	v_exp_f32_e32 v249, v51
	v_exp_f32_e32 v250, v52
	v_mfma_f32_32x32x16_bf16 v[32:47], v[140:143], v[170:173], v[32:47]
	v_exp_f32_e32 v251, v53
	v_exp_f32_e32 v252, v54
	v_exp_f32_e32 v234, v55
	v_cvt_pk_bf16_f32 v174, v246, v247
	v_cvt_pk_bf16_f32 v175, v248, v249
	v_cvt_pk_bf16_f32 v176, v250, v251
	v_cvt_pk_bf16_f32 v177, v252, v234
	v_mfma_f32_32x32x16_bf16 v[16:31], v[10:13], v[170:173], v[16:31]
	v_exp_f32_e32 v235, v56
	v_exp_f32_e32 v203, v57
	v_exp_f32_e32 v204, v58
	v_exp_f32_e32 v208, v59
	v_exp_f32_e32 v209, v60
	v_exp_f32_e32 v210, v61
	v_exp_f32_e32 v211, v62
	v_mfma_f32_32x32x16_bf16 v[32:47], v[136:139], v[174:177], v[32:47]
	v_exp_f32_e32 v214, v63
	v_cvt_pk_bf16_f32 v178, v235, v203
	v_cvt_pk_bf16_f32 v179, v204, v208
	v_cvt_pk_bf16_f32 v180, v209, v210
	v_cvt_pk_bf16_f32 v181, v211, v214
	s_andn2_b64 vcc, exec, s[2:3]
	v_mfma_f32_32x32x16_bf16 v[16:31], v[2:5], v[174:177], v[16:31]
	v_mfma_f32_32x32x16_bf16 v[32:47], v[132:135], v[178:181], v[32:47]
	v_mfma_f32_32x32x16_bf16 v[16:31], v[6:9], v[178:181], v[16:31]
	s_cbranch_vccnz .LBB0_180
	ds_write_b128 v157, v[104:107]
	s_and_saveexec_b64 s[2:3], s[38:39]
	ds_write_b128 v158, v[112:115]
	s_or_b64 exec, exec, s[2:3]
	ds_write_b128 v160, v[120:123] offset:13312
.LBB0_180:
	v_lshl_add_u64 v[244:245], v[244:245], 0, s[30:31]
	v_lshl_add_u64 v[236:237], v[236:237], 0, s[26:27]
	v_lshl_add_u64 v[238:239], v[238:239], 0, s[26:27]
	s_andn2_b64 vcc, exec, s[90:91]
	v_lshl_add_u64 v[240:241], v[240:241], 0, s[26:27]
	v_lshl_add_u64 v[242:243], v[242:243], 0, s[26:27]
	s_waitcnt lgkmcnt(0)
	s_barrier
	s_cbranch_vccz .Lpsep_c_exit
	s_mov_b32 s22, s15
	s_branch .LBB0_162
.Lpsep_c_exit:
	v_add_f32_e32 v162, 0, v184
	v_add_f32_e32 v163, 0, v246
	v_add_f32_e32 v162, v162, v185
	v_add_f32_e32 v163, v163, v247
	v_add_f32_e32 v162, v186, v162
	v_add_f32_e32 v163, v248, v163
	v_add_f32_e32 v162, v187, v162
	v_add_f32_e32 v163, v249, v163
	v_add_f32_e32 v162, v188, v162
	v_add_f32_e32 v163, v250, v163
	v_add_f32_e32 v162, v189, v162
	v_add_f32_e32 v163, v251, v163
	v_add_f32_e32 v162, v190, v162
	v_add_f32_e32 v163, v252, v163
	v_add_f32_e32 v162, v191, v162
	v_add_f32_e32 v163, v234, v163
	v_add_f32_e32 v162, v192, v162
	v_add_f32_e32 v163, v235, v163
	v_add_f32_e32 v162, v193, v162
	v_add_f32_e32 v163, v203, v163
	v_add_f32_e32 v162, v194, v162
	v_add_f32_e32 v163, v204, v163
	v_add_f32_e32 v162, v195, v162
	v_add_f32_e32 v163, v208, v163
	v_add_f32_e32 v162, v196, v162
	v_add_f32_e32 v163, v209, v163
	v_add_f32_e32 v162, v197, v162
	v_add_f32_e32 v163, v210, v163
	v_add_f32_e32 v162, v198, v162
	v_add_f32_e32 v163, v211, v163
	v_add_f32_e32 v162, v199, v162
	v_add_f32_e32 v163, v214, v163
	v_add_f32_e32 v162, v163, v162
	v_add_f32_e32 v0, v0, v162
	s_branch .LBB0_203

.LBB0_185:
	v_add_f32_e32 v50, 0, v50
	v_add_f32_e32 v34, 0, v34
	v_add_f32_e32 v50, v50, v51
	v_add_f32_e32 v34, v34, v35
	v_add_f32_e32 v35, v52, v50
	v_add_f32_e32 v34, v36, v34
	v_add_f32_e32 v35, v53, v35
	v_add_f32_e32 v34, v37, v34
	v_add_f32_e32 v35, v54, v35
	v_add_f32_e32 v34, v38, v34
	v_add_f32_e32 v35, v55, v35
	v_add_f32_e32 v34, v39, v34
	v_add_f32_e32 v35, v56, v35
	v_add_f32_e32 v34, v40, v34
	v_add_f32_e32 v35, v57, v35
	v_add_f32_e32 v34, v41, v34
	v_add_f32_e32 v35, v58, v35
	v_add_f32_e32 v34, v42, v34
	v_add_f32_e32 v35, v59, v35
	v_add_f32_e32 v34, v43, v34
	v_add_f32_e32 v35, v60, v35
	v_add_f32_e32 v34, v44, v34
	v_add_f32_e32 v35, v61, v35
	v_add_f32_e32 v34, v45, v34
	v_add_f32_e32 v35, v62, v35
	v_add_f32_e32 v34, v46, v34
	v_add_f32_e32 v35, v63, v35
	v_add_f32_e32 v34, v47, v34
	v_add_f32_e32 v35, v64, v35
	v_add_f32_e32 v34, v48, v34
	v_add_f32_e32 v35, v65, v35
	v_add_f32_e32 v34, v49, v34
	v_add_f32_e32 v34, v34, v35
	s_add_i32 s3, s3, 2
	v_add_f32_e32 v136, v128, v34
	v_lshl_add_u64 v[242:243], v[242:243], 0, s[30:31]
	s_cmp_lt_u32 s12, s2
	v_lshl_add_u64 v[238:239], v[238:239], 0, s[28:29]
	v_lshl_add_u64 v[240:241], v[240:241], 0, s[28:29]
	s_waitcnt lgkmcnt(0)
	s_barrier
	s_cbranch_scc0 .LBB0_196

.LBB0_190:
	v_exp_f32_e32 v50, v50
	v_exp_f32_e32 v51, v51
	v_exp_f32_e32 v52, v52
	v_exp_f32_e32 v53, v53
	v_exp_f32_e32 v54, v54
	v_exp_f32_e32 v55, v55
	v_exp_f32_e32 v56, v56
	v_exp_f32_e32 v57, v57
	v_cvt_pk_bf16_f32 v138, v50, v51
	v_cvt_pk_bf16_f32 v139, v52, v53
	v_cvt_pk_bf16_f32 v140, v54, v55
	v_cvt_pk_bf16_f32 v141, v56, v57
	v_exp_f32_e32 v58, v58
	v_exp_f32_e32 v59, v59
	s_waitcnt lgkmcnt(0)
	v_mfma_f32_32x32x16_bf16 v[2:17], v[118:121], v[138:141], v[2:17]
	v_exp_f32_e32 v60, v60
	v_exp_f32_e32 v61, v61
	v_exp_f32_e32 v62, v62
	v_exp_f32_e32 v63, v63
	v_exp_f32_e32 v64, v64
	v_exp_f32_e32 v65, v65
	v_cvt_pk_bf16_f32 v142, v58, v59
	v_mfma_f32_32x32x16_bf16 v[18:33], v[102:105], v[138:141], v[18:33]
	v_cvt_pk_bf16_f32 v143, v60, v61
	v_cvt_pk_bf16_f32 v144, v62, v63
	v_cvt_pk_bf16_f32 v145, v64, v65
	v_exp_f32_e32 v34, v34
	v_exp_f32_e32 v35, v35
	v_exp_f32_e32 v36, v36
	v_exp_f32_e32 v37, v37
	v_mfma_f32_32x32x16_bf16 v[2:17], v[114:117], v[142:145], v[2:17]
	v_exp_f32_e32 v38, v38
	v_exp_f32_e32 v39, v39
	v_exp_f32_e32 v40, v40
	v_exp_f32_e32 v41, v41
	v_cvt_pk_bf16_f32 v150, v34, v35
	v_cvt_pk_bf16_f32 v151, v36, v37
	v_cvt_pk_bf16_f32 v152, v38, v39
	v_mfma_f32_32x32x16_bf16 v[18:33], v[98:101], v[142:145], v[18:33]
	v_cvt_pk_bf16_f32 v153, v40, v41
	v_exp_f32_e32 v42, v42
	v_exp_f32_e32 v43, v43
	v_exp_f32_e32 v44, v44
	v_exp_f32_e32 v45, v45
	v_exp_f32_e32 v46, v46
	v_exp_f32_e32 v47, v47
	v_mfma_f32_32x32x16_bf16 v[2:17], v[110:113], v[150:153], v[2:17]
	v_exp_f32_e32 v48, v48
	v_exp_f32_e32 v49, v49
	v_cvt_pk_bf16_f32 v154, v42, v43
	v_cvt_pk_bf16_f32 v155, v44, v45
	v_cvt_pk_bf16_f32 v156, v46, v47
	v_cvt_pk_bf16_f32 v157, v48, v49
	s_cmp_ge_u32 s3, s2
	v_mfma_f32_32x32x16_bf16 v[18:33], v[90:93], v[150:153], v[18:33]
	s_waitcnt vmcnt(0)
	ds_write_b128 v123, v[82:85] offset:18432
	ds_write_b128 v122, v[86:89] offset:27648
	s_waitcnt lgkmcnt(0)
	s_barrier
	v_mfma_f32_32x32x16_bf16 v[2:17], v[106:109], v[154:157], v[2:17]
	v_mfma_f32_32x32x16_bf16 v[18:33], v[94:97], v[154:157], v[18:33]
	s_cbranch_scc1 .LBB0_192
	global_load_dwordx4 v[82:85], v[240:241], off
	global_load_dwordx4 v[86:89], v[242:243], off offset:128
